# attention: all 8 K-fragment ds_reads issued before the QK MFMAs with counted lgkmcnt waits; dead v_mov copies of softmax results removed
# speedup vs baseline: 1.0151x; 1.0041x over previous
.LBB0_1150:
	s_add_i32 s2, s42, 5
	s_min_i32 s72, s2, s68
	v_lshl_add_u32 v0, s43, 14, v200
	s_lshl_b64 s[2:3], s[72:73], 13
	v_readfirstlane_b32 s4, v0
	v_lshl_add_u64 v[110:111], v[104:105], 0, s[2:3]
	s_mov_b32 m0, s4
	v_add_u32_e32 v0, 0x2000, v0
	s_waitcnt vmcnt(6)
	s_barrier
	global_load_lds_dwordx4 v[110:111], off
	v_lshl_add_u64 v[110:111], v[106:107], 0, s[2:3]
	v_readfirstlane_b32 s2, v0
	s_mov_b32 m0, s2
	s_add_i32 s2, s45, 1
	global_load_lds_dwordx4 v[110:111], off
	s_cmp_lg_u32 s45, 5
	s_cselect_b32 s46, s2, 0
	s_cmp_lt_i32 s42, s68
	s_cselect_b64 s[40:41], -1, 0
	s_cmp_ge_i32 s42, s68
	s_mov_b64 s[10:11], 0
	s_cbranch_scc1 .LBB0_1153
	s_add_i32 s2, s42, 1
	v_sub_co_u32_e64 v108, vcc, s42, 31
	v_lshrrev_b32_e32 v0, s2, v102
	v_lshrrev_b32_e32 v108, v108, v103
	v_cndmask_b32_e32 v0, v108, v0, vcc
	v_and_b32_e32 v0, 1, v0
	v_cmp_ne_u32_e32 vcc, 0, v0
	s_cbranch_vccz .LBB0_1153
	v_lshl_add_u32 v0, s46, 14, v205
	v_add_u32_e32 v70, v0, v201
	ds_read_b128 v[66:69], v70
	ds_read_b128 v[82:85], v70 offset:4096
	v_add_u32_e32 v108, v0, v202
	ds_read_b128 v[118:121], v108
	ds_read_b128 v[122:125], v108 offset:4096
	v_add_u32_e32 v108, v0, v203
	ds_read_b128 v[126:129], v108
	ds_read_b128 v[130:133], v108 offset:4096
	v_add_u32_e32 v0, v0, v204
	ds_read_b128 v[134:137], v0
	ds_read_b128 v[138:141], v0 offset:4096
	s_mov_b64 s[10:11], -1
	s_waitcnt lgkmcnt(6)
	v_mfma_f32_32x32x16_bf16 v[66:81], v[66:69], v[162:165], 0
	v_mfma_f32_32x32x16_bf16 v[82:97], v[82:85], v[162:165], 0
	s_waitcnt lgkmcnt(4)
	v_mfma_f32_32x32x16_bf16 v[66:81], v[118:121], v[166:169], v[66:81]
	v_mfma_f32_32x32x16_bf16 v[82:97], v[122:125], v[166:169], v[82:97]
	s_waitcnt lgkmcnt(2)
	v_mfma_f32_32x32x16_bf16 v[66:81], v[126:129], v[170:173], v[66:81]
	v_mfma_f32_32x32x16_bf16 v[82:97], v[130:133], v[170:173], v[82:97]
	s_waitcnt lgkmcnt(0)
	v_mfma_f32_32x32x16_bf16 v[66:81], v[134:137], v[174:177], v[66:81]
	v_mfma_f32_32x32x16_bf16 v[82:97], v[138:141], v[174:177], v[82:97]

.LBB0_1160:
	v_max_f32_e32 v0, v117, v117
	v_max_f32_e32 v0, 0xefa18f08, v0
	v_cndmask_b32_e64 v116, v0, v198, s[2:3]
	v_sub_f32_e32 v0, v34, v116
	v_exp_f32_e32 v34, v0
	v_sub_f32_e32 v0, v50, v116
	v_exp_f32_e32 v50, v0
	v_sub_f32_e32 v0, v35, v116
	v_exp_f32_e32 v154, v0
	v_sub_f32_e32 v0, v51, v116
	v_exp_f32_e32 v0, v0
	v_sub_f32_e32 v35, v36, v116
	v_add_f32_e32 v155, v34, v50
	v_exp_f32_e32 v36, v35
	v_sub_f32_e32 v35, v52, v116
	v_pk_add_f32 v[110:111], v[154:155], v[0:1]
	v_exp_f32_e32 v52, v35
	v_sub_f32_e32 v35, v37, v116
	v_pk_add_f32 v[110:111], v[110:111], v[110:111] op_sel_hi:[0,1]
	v_exp_f32_e32 v156, v35
	v_sub_f32_e32 v35, v53, v116
	v_exp_f32_e32 v110, v35
	v_sub_f32_e32 v37, v38, v116
	v_add_f32_e32 v157, v36, v52
	v_exp_f32_e32 v38, v37
	v_sub_f32_e32 v37, v54, v116
	v_pk_add_f32 v[118:119], v[156:157], v[110:111]
	v_exp_f32_e32 v54, v37
	v_sub_f32_e32 v37, v39, v116
	v_pk_add_f32 v[158:159], v[118:119], v[118:119] op_sel_hi:[0,1]
	v_exp_f32_e32 v160, v37
	v_sub_f32_e32 v37, v55, v116
	v_exp_f32_e32 v158, v37
	v_sub_f32_e32 v37, v40, v116
	v_add_f32_e32 v161, v38, v54
	v_exp_f32_e32 v40, v37
	v_sub_f32_e32 v37, v56, v116
	v_pk_add_f32 v[126:127], v[160:161], v[158:159]
	v_exp_f32_e32 v56, v37
	v_sub_f32_e32 v37, v41, v116
	v_pk_add_f32 v[186:187], v[126:127], v[126:127] op_sel_hi:[0,1]
	v_exp_f32_e32 v188, v37
	v_sub_f32_e32 v37, v57, v116
	v_exp_f32_e32 v186, v37
	v_sub_f32_e32 v37, v42, v116
	v_add_f32_e32 v189, v40, v56
	v_exp_f32_e32 v42, v37
	v_sub_f32_e32 v37, v58, v116
	v_pk_add_f32 v[134:135], v[188:189], v[186:187]
	v_exp_f32_e32 v58, v37
	v_sub_f32_e32 v37, v43, v116
	v_pk_add_f32 v[190:191], v[134:135], v[134:135] op_sel_hi:[0,1]
	v_exp_f32_e32 v192, v37
	v_sub_f32_e32 v37, v59, v116
	v_exp_f32_e32 v190, v37
	v_sub_f32_e32 v37, v44, v116
	v_add_f32_e32 v193, v42, v58
	v_exp_f32_e32 v44, v37
	v_sub_f32_e32 v37, v60, v116
	v_pk_add_f32 v[142:143], v[192:193], v[190:191]
	v_exp_f32_e32 v60, v37
	v_sub_f32_e32 v37, v45, v116
	v_pk_add_f32 v[194:195], v[142:143], v[142:143] op_sel_hi:[0,1]
	v_exp_f32_e32 v224, v37
	v_sub_f32_e32 v37, v61, v116
	v_exp_f32_e32 v194, v37
	v_lshl_add_u32 v35, s45, 14, v112
	ds_read_b64_tr_b16 v[118:119], v35 offset:8192
	ds_read_b64_tr_b16 v[120:121], v35 offset:8704
	ds_read_b64_tr_b16 v[122:123], v35 offset:9216
	ds_read_b64_tr_b16 v[124:125], v35 offset:9728
	ds_read_b64_tr_b16 v[126:127], v35 offset:12288
	ds_read_b64_tr_b16 v[128:129], v35 offset:12800
	ds_read_b64_tr_b16 v[130:131], v35 offset:13312
	ds_read_b64_tr_b16 v[132:133], v35 offset:13824
	ds_read_b64_tr_b16 v[134:135], v35 offset:10240
	ds_read_b64_tr_b16 v[136:137], v35 offset:10752
	ds_read_b64_tr_b16 v[138:139], v35 offset:11264
	ds_read_b64_tr_b16 v[140:141], v35 offset:11776
	ds_read_b64_tr_b16 v[142:143], v35 offset:14336
	ds_read_b64_tr_b16 v[144:145], v35 offset:14848
	ds_read_b64_tr_b16 v[146:147], v35 offset:15360
	ds_read_b64_tr_b16 v[148:149], v35 offset:15872
	v_add_f32_e32 v225, v44, v60
	v_sub_f32_e32 v35, v46, v116
	v_pk_add_f32 v[150:151], v[224:225], v[194:195]
	v_exp_f32_e32 v46, v35
	v_sub_f32_e32 v35, v62, v116
	v_pk_add_f32 v[226:227], v[150:151], v[150:151] op_sel_hi:[0,1]
	v_cvt_pk_bf16_f32 v150, v34, v154
	v_cvt_pk_bf16_f32 v151, v36, v156
	v_cvt_pk_bf16_f32 v152, v38, v160
	v_cvt_pk_bf16_f32 v153, v40, v188
	v_exp_f32_e32 v62, v35
	v_sub_f32_e32 v35, v47, v116
	s_waitcnt lgkmcnt(0)
	v_mfma_f32_32x32x16_bf16 v[2:17], v[118:121], v[150:153], v[2:17]
	v_exp_f32_e32 v228, v35
	v_sub_f32_e32 v35, v63, v116
	v_exp_f32_e32 v226, v35
	v_sub_f32_e32 v35, v48, v116
	v_exp_f32_e32 v48, v35
	v_sub_f32_e32 v35, v49, v116
	v_exp_f32_e32 v49, v35
	v_mfma_f32_32x32x16_bf16 v[18:33], v[126:129], v[150:153], v[18:33]
	v_cvt_pk_bf16_f32 v118, v42, v192
	v_cvt_pk_bf16_f32 v119, v44, v224
	v_cvt_pk_bf16_f32 v120, v46, v228
	v_cvt_pk_bf16_f32 v121, v48, v49
	v_sub_f32_e32 v35, v64, v116
	v_exp_f32_e32 v64, v35
	v_sub_f32_e32 v35, v65, v116
	v_mfma_f32_32x32x16_bf16 v[2:17], v[122:125], v[118:121], v[2:17]
	v_exp_f32_e32 v65, v35
	v_add_f32_e32 v229, v46, v62
	v_pk_add_f32 v[122:123], v[228:229], v[226:227]
	v_add_f32_e32 v111, v48, v64
	v_pk_add_f32 v[122:123], v[122:123], v[122:123] op_sel_hi:[0,1]
	v_mov_b32_e32 v122, v65
	v_mfma_f32_32x32x16_bf16 v[18:33], v[130:133], v[118:121], v[18:33]
	v_cvt_pk_bf16_f32 v118, v50, v0
	v_cvt_pk_bf16_f32 v119, v52, v110
	v_cvt_pk_bf16_f32 v120, v54, v158
	v_cvt_pk_bf16_f32 v121, v56, v186
	v_mov_b32_e32 v110, v49
	v_pk_add_f32 v[110:111], v[110:111], v[122:123]
	v_mfma_f32_32x32x16_bf16 v[2:17], v[134:137], v[118:121], v[2:17]
	v_add_f32_e32 v0, v110, v111
	v_fmac_f32_e32 v0, v115, v108
	v_mfma_f32_32x32x16_bf16 v[18:33], v[142:145], v[118:121], v[18:33]
	v_cvt_pk_bf16_f32 v118, v58, v190
	v_cvt_pk_bf16_f32 v119, v60, v194
	v_cvt_pk_bf16_f32 v120, v62, v226
	v_cvt_pk_bf16_f32 v121, v64, v65
	s_nop 1
	v_mfma_f32_32x32x16_bf16 v[2:17], v[138:141], v[118:121], v[2:17]
	v_mov_b32_e32 v115, v0
	v_mfma_f32_32x32x16_bf16 v[18:33], v[146:149], v[118:121], v[18:33]
	s_branch .LBB0_1162

.LBB0_1162:
	s_add_i32 s2, s43, 1
	s_cmp_lg_u32 s43, 5
	s_cselect_b32 s43, s2, 0
	s_andn2_b64 vcc, exec, s[40:41]
	s_cbranch_vccnz .LBB0_1149
	s_add_i32 s2, s42, 6
	s_min_i32 s72, s2, s68
	v_lshl_add_u32 v0, s43, 14, v200
	s_lshl_b64 s[2:3], s[72:73], 13
	v_readfirstlane_b32 s4, v0
	v_lshl_add_u64 v[110:111], v[104:105], 0, s[2:3]
	s_mov_b32 m0, s4
	v_add_u32_e32 v0, 0x2000, v0
	s_waitcnt vmcnt(6)
	s_barrier
	global_load_lds_dwordx4 v[110:111], off
	v_lshl_add_u64 v[110:111], v[106:107], 0, s[2:3]
	v_readfirstlane_b32 s2, v0
	s_mov_b32 m0, s2
	s_add_i32 s40, s42, 1
	global_load_lds_dwordx4 v[110:111], off
	s_add_i32 s2, s46, 1
	s_cmp_lg_u32 s46, 5
	s_cselect_b32 s45, s2, 0
	s_cmp_ge_i32 s40, s68
	s_mov_b64 s[38:39], 0
	s_cbranch_scc1 .LBB0_1166
	s_cmp_lt_u32 s40, 31
	s_cselect_b64 vcc, -1, 0
	s_add_i32 s2, s42, 2
	v_lshrrev_b32_e32 v0, s2, v102
	s_sub_i32 s2, s42, 30
	v_lshrrev_b32_e32 v108, s2, v103
	v_cndmask_b32_e32 v0, v108, v0, vcc
	v_and_b32_e32 v0, 1, v0
	v_cmp_ne_u32_e32 vcc, 0, v0
	s_cbranch_vccz .LBB0_1166
	v_lshl_add_u32 v0, s45, 14, v205
	v_add_u32_e32 v38, v0, v201
	ds_read_b128 v[34:37], v38
	ds_read_b128 v[50:53], v38 offset:4096
	v_add_u32_e32 v108, v0, v202
	ds_read_b128 v[118:121], v108
	ds_read_b128 v[122:125], v108 offset:4096
	v_add_u32_e32 v108, v0, v203
	ds_read_b128 v[126:129], v108
	ds_read_b128 v[130:133], v108 offset:4096
	v_add_u32_e32 v0, v0, v204
	ds_read_b128 v[134:137], v0
	ds_read_b128 v[138:141], v0 offset:4096
	s_mov_b64 s[38:39], -1
	s_waitcnt lgkmcnt(6)
	v_mfma_f32_32x32x16_bf16 v[34:49], v[34:37], v[162:165], 0
	v_mfma_f32_32x32x16_bf16 v[50:65], v[50:53], v[162:165], 0
	s_waitcnt lgkmcnt(4)
	v_mfma_f32_32x32x16_bf16 v[34:49], v[118:121], v[166:169], v[34:49]
	v_mfma_f32_32x32x16_bf16 v[50:65], v[122:125], v[166:169], v[50:65]
	s_waitcnt lgkmcnt(2)
	v_mfma_f32_32x32x16_bf16 v[34:49], v[126:129], v[170:173], v[34:49]
	v_mfma_f32_32x32x16_bf16 v[50:65], v[130:133], v[170:173], v[50:65]
	s_waitcnt lgkmcnt(0)
	v_mfma_f32_32x32x16_bf16 v[34:49], v[134:137], v[174:177], v[34:49]
	v_mfma_f32_32x32x16_bf16 v[50:65], v[138:141], v[174:177], v[50:65]

.LBB0_1173:
	v_max_f32_e32 v0, v116, v116
	v_max_f32_e32 v0, 0xefa18f08, v0
	v_cndmask_b32_e64 v117, v0, v198, s[2:3]
	v_sub_f32_e32 v0, v66, v117
	v_exp_f32_e32 v66, v0
	v_sub_f32_e32 v0, v82, v117
	v_exp_f32_e32 v82, v0
	v_sub_f32_e32 v0, v67, v117
	v_exp_f32_e32 v154, v0
	v_sub_f32_e32 v0, v83, v117
	v_exp_f32_e32 v0, v0
	v_sub_f32_e32 v67, v68, v117
	v_add_f32_e32 v155, v66, v82
	v_exp_f32_e32 v68, v67
	v_sub_f32_e32 v67, v84, v117
	v_pk_add_f32 v[110:111], v[154:155], v[0:1]
	v_exp_f32_e32 v84, v67
	v_sub_f32_e32 v67, v69, v117
	v_pk_add_f32 v[110:111], v[110:111], v[110:111] op_sel_hi:[0,1]
	v_exp_f32_e32 v156, v67
	v_sub_f32_e32 v67, v85, v117
	v_exp_f32_e32 v110, v67
	v_sub_f32_e32 v69, v70, v117
	v_add_f32_e32 v157, v68, v84
	v_exp_f32_e32 v70, v69
	v_sub_f32_e32 v69, v86, v117
	v_pk_add_f32 v[118:119], v[156:157], v[110:111]
	v_exp_f32_e32 v86, v69
	v_sub_f32_e32 v69, v71, v117
	v_pk_add_f32 v[158:159], v[118:119], v[118:119] op_sel_hi:[0,1]
	v_exp_f32_e32 v160, v69
	v_sub_f32_e32 v69, v87, v117
	v_exp_f32_e32 v158, v69
	v_sub_f32_e32 v69, v72, v117
	v_add_f32_e32 v161, v70, v86
	v_exp_f32_e32 v72, v69
	v_sub_f32_e32 v69, v88, v117
	v_pk_add_f32 v[126:127], v[160:161], v[158:159]
	v_exp_f32_e32 v88, v69
	v_sub_f32_e32 v69, v73, v117
	v_pk_add_f32 v[186:187], v[126:127], v[126:127] op_sel_hi:[0,1]
	v_exp_f32_e32 v188, v69
	v_sub_f32_e32 v69, v89, v117
	v_exp_f32_e32 v186, v69
	v_sub_f32_e32 v69, v74, v117
	v_add_f32_e32 v189, v72, v88
	v_exp_f32_e32 v74, v69
	v_sub_f32_e32 v69, v90, v117
	v_pk_add_f32 v[134:135], v[188:189], v[186:187]
	v_exp_f32_e32 v90, v69
	v_sub_f32_e32 v69, v75, v117
	v_pk_add_f32 v[190:191], v[134:135], v[134:135] op_sel_hi:[0,1]
	v_exp_f32_e32 v192, v69
	v_sub_f32_e32 v69, v91, v117
	v_exp_f32_e32 v190, v69
	v_sub_f32_e32 v69, v76, v117
	v_add_f32_e32 v193, v74, v90
	v_exp_f32_e32 v76, v69
	v_sub_f32_e32 v69, v92, v117
	v_pk_add_f32 v[142:143], v[192:193], v[190:191]
	v_exp_f32_e32 v92, v69
	v_sub_f32_e32 v69, v77, v117
	v_pk_add_f32 v[194:195], v[142:143], v[142:143] op_sel_hi:[0,1]
	v_exp_f32_e32 v224, v69
	v_sub_f32_e32 v69, v93, v117
	v_exp_f32_e32 v194, v69
	v_lshl_add_u32 v67, s46, 14, v112
	ds_read_b64_tr_b16 v[118:119], v67 offset:8192
	ds_read_b64_tr_b16 v[120:121], v67 offset:8704
	ds_read_b64_tr_b16 v[122:123], v67 offset:9216
	ds_read_b64_tr_b16 v[124:125], v67 offset:9728
	ds_read_b64_tr_b16 v[126:127], v67 offset:12288
	ds_read_b64_tr_b16 v[128:129], v67 offset:12800
	ds_read_b64_tr_b16 v[130:131], v67 offset:13312
	ds_read_b64_tr_b16 v[132:133], v67 offset:13824
	ds_read_b64_tr_b16 v[134:135], v67 offset:10240
	ds_read_b64_tr_b16 v[136:137], v67 offset:10752
	ds_read_b64_tr_b16 v[138:139], v67 offset:11264
	ds_read_b64_tr_b16 v[140:141], v67 offset:11776
	ds_read_b64_tr_b16 v[142:143], v67 offset:14336
	ds_read_b64_tr_b16 v[144:145], v67 offset:14848
	ds_read_b64_tr_b16 v[146:147], v67 offset:15360
	ds_read_b64_tr_b16 v[148:149], v67 offset:15872
	v_add_f32_e32 v225, v76, v92
	v_sub_f32_e32 v67, v78, v117
	v_pk_add_f32 v[150:151], v[224:225], v[194:195]
	v_exp_f32_e32 v78, v67
	v_sub_f32_e32 v67, v94, v117
	v_pk_add_f32 v[226:227], v[150:151], v[150:151] op_sel_hi:[0,1]
	v_cvt_pk_bf16_f32 v150, v66, v154
	v_cvt_pk_bf16_f32 v151, v68, v156
	v_cvt_pk_bf16_f32 v152, v70, v160
	v_cvt_pk_bf16_f32 v153, v72, v188
	v_exp_f32_e32 v94, v67
	v_sub_f32_e32 v67, v79, v117
	s_waitcnt lgkmcnt(0)
	v_mfma_f32_32x32x16_bf16 v[2:17], v[118:121], v[150:153], v[2:17]
	v_exp_f32_e32 v228, v67
	v_sub_f32_e32 v67, v95, v117
	v_exp_f32_e32 v226, v67
	v_sub_f32_e32 v67, v80, v117
	v_exp_f32_e32 v80, v67
	v_sub_f32_e32 v67, v81, v117
	v_exp_f32_e32 v81, v67
	v_mfma_f32_32x32x16_bf16 v[18:33], v[126:129], v[150:153], v[18:33]
	v_cvt_pk_bf16_f32 v118, v74, v192
	v_cvt_pk_bf16_f32 v119, v76, v224
	v_cvt_pk_bf16_f32 v120, v78, v228
	v_cvt_pk_bf16_f32 v121, v80, v81
	v_sub_f32_e32 v67, v96, v117
	v_exp_f32_e32 v96, v67
	v_sub_f32_e32 v67, v97, v117
	v_mfma_f32_32x32x16_bf16 v[2:17], v[122:125], v[118:121], v[2:17]
	v_exp_f32_e32 v97, v67
	v_add_f32_e32 v229, v78, v94
	v_pk_add_f32 v[122:123], v[228:229], v[226:227]
	v_add_f32_e32 v111, v80, v96
	v_pk_add_f32 v[122:123], v[122:123], v[122:123] op_sel_hi:[0,1]
	v_mov_b32_e32 v122, v97
	v_mfma_f32_32x32x16_bf16 v[18:33], v[130:133], v[118:121], v[18:33]
	v_cvt_pk_bf16_f32 v118, v82, v0
	v_cvt_pk_bf16_f32 v119, v84, v110
	v_cvt_pk_bf16_f32 v120, v86, v158
	v_cvt_pk_bf16_f32 v121, v88, v186
	v_mov_b32_e32 v110, v81
	v_pk_add_f32 v[110:111], v[110:111], v[122:123]
	v_mfma_f32_32x32x16_bf16 v[2:17], v[134:137], v[118:121], v[2:17]
	v_add_f32_e32 v0, v110, v111
	v_fmac_f32_e32 v0, v115, v108
	v_mfma_f32_32x32x16_bf16 v[18:33], v[142:145], v[118:121], v[18:33]
	v_cvt_pk_bf16_f32 v118, v90, v190
	v_cvt_pk_bf16_f32 v119, v92, v194
	v_cvt_pk_bf16_f32 v120, v94, v226
	v_cvt_pk_bf16_f32 v121, v96, v97
	s_nop 1
	v_mfma_f32_32x32x16_bf16 v[2:17], v[138:141], v[118:121], v[2:17]
	v_mov_b32_e32 v115, v0
	v_mfma_f32_32x32x16_bf16 v[18:33], v[146:149], v[118:121], v[18:33]
	s_branch .LBB0_1175

.LBB0_1181:
	s_add_i32 s0, s40, 5
	s_min_i32 s0, s0, s68
	s_ashr_i32 s1, s0, 31
	v_lshl_add_u32 v0, s43, 14, v200
	s_lshl_b64 s[0:1], s[0:1], 13
	v_readfirstlane_b32 s2, v0
	v_lshl_add_u64 v[104:105], v[98:99], 0, s[0:1]
	s_mov_b32 m0, s2
	v_add_u32_e32 v0, 0x2000, v0
	s_waitcnt vmcnt(6)
	s_barrier
	global_load_lds_dwordx4 v[104:105], off
	v_lshl_add_u64 v[104:105], v[100:101], 0, s[0:1]
	v_readfirstlane_b32 s0, v0
	s_mov_b32 m0, s0
	s_add_i32 s0, s44, 1
	global_load_lds_dwordx4 v[104:105], off
	s_cmp_lg_u32 s44, 5
	s_cselect_b32 s45, s0, 0
	s_cmp_lt_i32 s40, s68
	s_cselect_b64 s[10:11], -1, 0
	s_cmp_ge_i32 s40, s68
	s_cbranch_scc1 .LBB0_1183
	v_lshl_add_u32 v0, s45, 14, v205
	v_add_u32_e32 v70, v0, v201
	ds_read_b128 v[66:69], v70
	ds_read_b128 v[82:85], v70 offset:4096
	v_add_u32_e32 v102, v0, v202
	ds_read_b128 v[114:117], v102
	ds_read_b128 v[118:121], v102 offset:4096
	v_add_u32_e32 v102, v0, v203
	ds_read_b128 v[122:125], v102
	ds_read_b128 v[126:129], v102 offset:4096
	v_add_u32_e32 v0, v0, v204
	ds_read_b128 v[130:133], v0
	ds_read_b128 v[134:137], v0 offset:4096
	s_waitcnt lgkmcnt(6)
	v_mfma_f32_32x32x16_bf16 v[66:81], v[66:69], v[162:165], 0
	v_mfma_f32_32x32x16_bf16 v[82:97], v[82:85], v[162:165], 0
	s_waitcnt lgkmcnt(4)
	v_mfma_f32_32x32x16_bf16 v[66:81], v[114:117], v[166:169], v[66:81]
	v_mfma_f32_32x32x16_bf16 v[82:97], v[118:121], v[166:169], v[82:97]
	s_waitcnt lgkmcnt(2)
	v_mfma_f32_32x32x16_bf16 v[66:81], v[122:125], v[170:173], v[66:81]
	v_mfma_f32_32x32x16_bf16 v[82:97], v[126:129], v[170:173], v[82:97]
	s_waitcnt lgkmcnt(0)
	v_mfma_f32_32x32x16_bf16 v[66:81], v[130:133], v[174:177], v[66:81]
	v_mfma_f32_32x32x16_bf16 v[82:97], v[134:137], v[174:177], v[82:97]

.LBB0_1190:
	v_max_f32_e32 v0, v108, v108
	v_max_f32_e32 v107, 0xefa18f08, v0
	v_sub_f32_e32 v0, v34, v107
	v_exp_f32_e32 v34, v0
	v_sub_f32_e32 v0, v50, v107
	v_exp_f32_e32 v50, v0
	v_sub_f32_e32 v0, v35, v107
	v_exp_f32_e32 v110, v0
	v_sub_f32_e32 v0, v51, v107
	v_exp_f32_e32 v0, v0
	v_sub_f32_e32 v35, v36, v107
	v_add_f32_e32 v111, v34, v50
	v_exp_f32_e32 v36, v35
	v_sub_f32_e32 v35, v52, v107
	v_pk_add_f32 v[104:105], v[110:111], v[0:1]
	v_exp_f32_e32 v52, v35
	v_sub_f32_e32 v35, v37, v107
	v_pk_add_f32 v[104:105], v[104:105], v[104:105] op_sel_hi:[0,1]
	v_exp_f32_e32 v150, v35
	v_sub_f32_e32 v35, v53, v107
	v_exp_f32_e32 v104, v35
	v_sub_f32_e32 v37, v38, v107
	v_add_f32_e32 v151, v36, v52
	v_exp_f32_e32 v38, v37
	v_sub_f32_e32 v37, v54, v107
	v_pk_add_f32 v[114:115], v[150:151], v[104:105]
	v_exp_f32_e32 v54, v37
	v_sub_f32_e32 v37, v39, v107
	v_pk_add_f32 v[152:153], v[114:115], v[114:115] op_sel_hi:[0,1]
	v_exp_f32_e32 v154, v37
	v_sub_f32_e32 v37, v55, v107
	v_exp_f32_e32 v152, v37
	v_sub_f32_e32 v37, v40, v107
	v_add_f32_e32 v155, v38, v54
	v_exp_f32_e32 v40, v37
	v_sub_f32_e32 v37, v56, v107
	v_pk_add_f32 v[122:123], v[154:155], v[152:153]
	v_exp_f32_e32 v56, v37
	v_sub_f32_e32 v37, v41, v107
	v_pk_add_f32 v[156:157], v[122:123], v[122:123] op_sel_hi:[0,1]
	v_exp_f32_e32 v158, v37
	v_sub_f32_e32 v37, v57, v107
	v_exp_f32_e32 v156, v37
	v_sub_f32_e32 v37, v42, v107
	v_add_f32_e32 v159, v40, v56
	v_exp_f32_e32 v42, v37
	v_sub_f32_e32 v37, v58, v107
	v_pk_add_f32 v[130:131], v[158:159], v[156:157]
	v_exp_f32_e32 v58, v37
	v_sub_f32_e32 v37, v43, v107
	v_pk_add_f32 v[160:161], v[130:131], v[130:131] op_sel_hi:[0,1]
	v_exp_f32_e32 v186, v37
	v_sub_f32_e32 v37, v59, v107
	v_exp_f32_e32 v160, v37
	v_sub_f32_e32 v37, v44, v107
	v_add_f32_e32 v187, v42, v58
	v_exp_f32_e32 v44, v37
	v_sub_f32_e32 v37, v60, v107
	v_pk_add_f32 v[138:139], v[186:187], v[160:161]
	v_exp_f32_e32 v60, v37
	v_sub_f32_e32 v37, v45, v107
	v_pk_add_f32 v[188:189], v[138:139], v[138:139] op_sel_hi:[0,1]
	v_exp_f32_e32 v190, v37
	v_sub_f32_e32 v37, v61, v107
	v_exp_f32_e32 v188, v37
	v_lshl_add_u32 v35, s44, 14, v112
	ds_read_b64_tr_b16 v[114:115], v35 offset:8192
	ds_read_b64_tr_b16 v[116:117], v35 offset:8704
	ds_read_b64_tr_b16 v[118:119], v35 offset:9216
	ds_read_b64_tr_b16 v[120:121], v35 offset:9728
	ds_read_b64_tr_b16 v[122:123], v35 offset:12288
	ds_read_b64_tr_b16 v[124:125], v35 offset:12800
	ds_read_b64_tr_b16 v[126:127], v35 offset:13312
	ds_read_b64_tr_b16 v[128:129], v35 offset:13824
	ds_read_b64_tr_b16 v[130:131], v35 offset:10240
	ds_read_b64_tr_b16 v[132:133], v35 offset:10752
	ds_read_b64_tr_b16 v[134:135], v35 offset:11264
	ds_read_b64_tr_b16 v[136:137], v35 offset:11776
	ds_read_b64_tr_b16 v[138:139], v35 offset:14336
	ds_read_b64_tr_b16 v[140:141], v35 offset:14848
	ds_read_b64_tr_b16 v[142:143], v35 offset:15360
	ds_read_b64_tr_b16 v[144:145], v35 offset:15872
	v_add_f32_e32 v191, v44, v60
	v_sub_f32_e32 v35, v46, v107
	v_pk_add_f32 v[146:147], v[190:191], v[188:189]
	v_exp_f32_e32 v46, v35
	v_sub_f32_e32 v35, v62, v107
	v_pk_add_f32 v[192:193], v[146:147], v[146:147] op_sel_hi:[0,1]
	v_cvt_pk_bf16_f32 v146, v34, v110
	v_cvt_pk_bf16_f32 v147, v36, v150
	v_cvt_pk_bf16_f32 v148, v38, v154
	v_cvt_pk_bf16_f32 v149, v40, v158
	v_exp_f32_e32 v62, v35
	v_sub_f32_e32 v35, v47, v107
	s_waitcnt lgkmcnt(0)
	v_mfma_f32_32x32x16_bf16 v[18:33], v[114:117], v[146:149], v[18:33]
	v_exp_f32_e32 v194, v35
	v_sub_f32_e32 v35, v63, v107
	v_exp_f32_e32 v192, v35
	v_sub_f32_e32 v35, v48, v107
	v_exp_f32_e32 v48, v35
	v_sub_f32_e32 v35, v49, v107
	v_exp_f32_e32 v49, v35
	v_mfma_f32_32x32x16_bf16 v[2:17], v[122:125], v[146:149], v[2:17]
	v_cvt_pk_bf16_f32 v114, v42, v186
	v_cvt_pk_bf16_f32 v115, v44, v190
	v_cvt_pk_bf16_f32 v116, v46, v194
	v_cvt_pk_bf16_f32 v117, v48, v49
	v_sub_f32_e32 v35, v64, v107
	v_exp_f32_e32 v64, v35
	v_sub_f32_e32 v35, v65, v107
	v_mfma_f32_32x32x16_bf16 v[18:33], v[118:121], v[114:117], v[18:33]
	v_exp_f32_e32 v65, v35
	v_add_f32_e32 v195, v46, v62
	v_pk_add_f32 v[118:119], v[194:195], v[192:193]
	v_add_f32_e32 v105, v48, v64
	v_pk_add_f32 v[118:119], v[118:119], v[118:119] op_sel_hi:[0,1]
	v_mov_b32_e32 v118, v65
	v_mfma_f32_32x32x16_bf16 v[2:17], v[126:129], v[114:117], v[2:17]
	v_cvt_pk_bf16_f32 v114, v50, v0
	v_cvt_pk_bf16_f32 v115, v52, v104
	v_cvt_pk_bf16_f32 v116, v54, v152
	v_cvt_pk_bf16_f32 v117, v56, v156
	v_mov_b32_e32 v104, v49
	v_pk_add_f32 v[104:105], v[104:105], v[118:119]
	v_mfma_f32_32x32x16_bf16 v[18:33], v[130:133], v[114:117], v[18:33]
	v_add_f32_e32 v0, v104, v105
	v_fmac_f32_e32 v0, v106, v102
	v_mfma_f32_32x32x16_bf16 v[2:17], v[138:141], v[114:117], v[2:17]
	v_cvt_pk_bf16_f32 v114, v58, v160
	v_cvt_pk_bf16_f32 v115, v60, v188
	v_cvt_pk_bf16_f32 v116, v62, v192
	v_cvt_pk_bf16_f32 v117, v64, v65
	s_nop 1
	v_mfma_f32_32x32x16_bf16 v[18:33], v[134:137], v[114:117], v[18:33]
	v_mov_b32_e32 v106, v0
	v_mfma_f32_32x32x16_bf16 v[2:17], v[142:145], v[114:117], v[2:17]
	s_branch .LBB0_1192

.LBB0_1192:
	s_add_i32 s0, s43, 1
	s_cmp_lg_u32 s43, 5
	s_cselect_b32 s43, s0, 0
	s_andn2_b64 vcc, exec, s[10:11]
	s_cbranch_vccnz .LBB0_1179
	s_add_i32 s0, s40, 6
	s_min_i32 s0, s0, s68
	s_ashr_i32 s1, s0, 31
	v_lshl_add_u32 v0, s43, 14, v200
	s_lshl_b64 s[0:1], s[0:1], 13
	v_readfirstlane_b32 s2, v0
	v_lshl_add_u64 v[104:105], v[98:99], 0, s[0:1]
	s_mov_b32 m0, s2
	v_add_u32_e32 v0, 0x2000, v0
	s_waitcnt vmcnt(6)
	s_barrier
	global_load_lds_dwordx4 v[104:105], off
	v_lshl_add_u64 v[104:105], v[100:101], 0, s[0:1]
	v_readfirstlane_b32 s0, v0
	s_mov_b32 m0, s0
	s_add_i32 s0, s40, 1
	global_load_lds_dwordx4 v[104:105], off
	s_add_i32 s1, s45, 1
	s_cmp_lg_u32 s45, 5
	s_cselect_b32 s44, s1, 0
	s_cmp_lt_i32 s0, s68
	s_cselect_b64 s[36:37], -1, 0
	s_cmp_ge_i32 s0, s68
	s_cbranch_scc1 .LBB0_1195
	v_lshl_add_u32 v0, s44, 14, v205
	v_add_u32_e32 v38, v0, v201
	ds_read_b128 v[34:37], v38
	ds_read_b128 v[50:53], v38 offset:4096
	v_add_u32_e32 v102, v0, v202
	ds_read_b128 v[114:117], v102
	ds_read_b128 v[118:121], v102 offset:4096
	v_add_u32_e32 v102, v0, v203
	ds_read_b128 v[122:125], v102
	ds_read_b128 v[126:129], v102 offset:4096
	v_add_u32_e32 v0, v0, v204
	ds_read_b128 v[130:133], v0
	ds_read_b128 v[134:137], v0 offset:4096
	s_waitcnt lgkmcnt(6)
	v_mfma_f32_32x32x16_bf16 v[34:49], v[34:37], v[162:165], 0
	v_mfma_f32_32x32x16_bf16 v[50:65], v[50:53], v[162:165], 0
	s_waitcnt lgkmcnt(4)
	v_mfma_f32_32x32x16_bf16 v[34:49], v[114:117], v[166:169], v[34:49]
	v_mfma_f32_32x32x16_bf16 v[50:65], v[118:121], v[166:169], v[50:65]
	s_waitcnt lgkmcnt(2)
	v_mfma_f32_32x32x16_bf16 v[34:49], v[122:125], v[170:173], v[34:49]
	v_mfma_f32_32x32x16_bf16 v[50:65], v[126:129], v[170:173], v[50:65]
	s_waitcnt lgkmcnt(0)
	v_mfma_f32_32x32x16_bf16 v[34:49], v[130:133], v[174:177], v[34:49]
	v_mfma_f32_32x32x16_bf16 v[50:65], v[134:137], v[174:177], v[50:65]

.LBB0_1201:
	v_max_f32_e32 v0, v107, v107
	v_max_f32_e32 v108, 0xefa18f08, v0
	v_sub_f32_e32 v0, v66, v108
	v_exp_f32_e32 v66, v0
	v_sub_f32_e32 v0, v82, v108
	v_exp_f32_e32 v82, v0
	v_sub_f32_e32 v0, v67, v108
	v_exp_f32_e32 v110, v0
	v_sub_f32_e32 v0, v83, v108
	v_exp_f32_e32 v0, v0
	v_sub_f32_e32 v67, v68, v108
	v_add_f32_e32 v111, v66, v82
	v_exp_f32_e32 v68, v67
	v_sub_f32_e32 v67, v84, v108
	v_pk_add_f32 v[104:105], v[110:111], v[0:1]
	v_exp_f32_e32 v84, v67
	v_sub_f32_e32 v67, v69, v108
	v_pk_add_f32 v[104:105], v[104:105], v[104:105] op_sel_hi:[0,1]
	v_exp_f32_e32 v150, v67
	v_sub_f32_e32 v67, v85, v108
	v_exp_f32_e32 v104, v67
	v_sub_f32_e32 v69, v70, v108
	v_add_f32_e32 v151, v68, v84
	v_exp_f32_e32 v70, v69
	v_sub_f32_e32 v69, v86, v108
	v_pk_add_f32 v[114:115], v[150:151], v[104:105]
	v_exp_f32_e32 v86, v69
	v_sub_f32_e32 v69, v71, v108
	v_pk_add_f32 v[152:153], v[114:115], v[114:115] op_sel_hi:[0,1]
	v_exp_f32_e32 v154, v69
	v_sub_f32_e32 v69, v87, v108
	v_exp_f32_e32 v152, v69
	v_sub_f32_e32 v69, v72, v108
	v_add_f32_e32 v155, v70, v86
	v_exp_f32_e32 v72, v69
	v_sub_f32_e32 v69, v88, v108
	v_pk_add_f32 v[122:123], v[154:155], v[152:153]
	v_exp_f32_e32 v88, v69
	v_sub_f32_e32 v69, v73, v108
	v_pk_add_f32 v[156:157], v[122:123], v[122:123] op_sel_hi:[0,1]
	v_exp_f32_e32 v158, v69
	v_sub_f32_e32 v69, v89, v108
	v_exp_f32_e32 v156, v69
	v_sub_f32_e32 v69, v74, v108
	v_add_f32_e32 v159, v72, v88
	v_exp_f32_e32 v74, v69
	v_sub_f32_e32 v69, v90, v108
	v_pk_add_f32 v[130:131], v[158:159], v[156:157]
	v_exp_f32_e32 v90, v69
	v_sub_f32_e32 v69, v75, v108
	v_pk_add_f32 v[160:161], v[130:131], v[130:131] op_sel_hi:[0,1]
	v_exp_f32_e32 v186, v69
	v_sub_f32_e32 v69, v91, v108
	v_exp_f32_e32 v160, v69
	v_sub_f32_e32 v69, v76, v108
	v_add_f32_e32 v187, v74, v90
	v_exp_f32_e32 v76, v69
	v_sub_f32_e32 v69, v92, v108
	v_pk_add_f32 v[138:139], v[186:187], v[160:161]
	v_exp_f32_e32 v92, v69
	v_sub_f32_e32 v69, v77, v108
	v_pk_add_f32 v[188:189], v[138:139], v[138:139] op_sel_hi:[0,1]
	v_exp_f32_e32 v190, v69
	v_sub_f32_e32 v69, v93, v108
	v_exp_f32_e32 v188, v69
	v_lshl_add_u32 v67, s45, 14, v112
	ds_read_b64_tr_b16 v[114:115], v67 offset:8192
	ds_read_b64_tr_b16 v[116:117], v67 offset:8704
	ds_read_b64_tr_b16 v[118:119], v67 offset:9216
	ds_read_b64_tr_b16 v[120:121], v67 offset:9728
	ds_read_b64_tr_b16 v[122:123], v67 offset:12288
	ds_read_b64_tr_b16 v[124:125], v67 offset:12800
	ds_read_b64_tr_b16 v[126:127], v67 offset:13312
	ds_read_b64_tr_b16 v[128:129], v67 offset:13824
	ds_read_b64_tr_b16 v[130:131], v67 offset:10240
	ds_read_b64_tr_b16 v[132:133], v67 offset:10752
	ds_read_b64_tr_b16 v[134:135], v67 offset:11264
	ds_read_b64_tr_b16 v[136:137], v67 offset:11776
	ds_read_b64_tr_b16 v[138:139], v67 offset:14336
	ds_read_b64_tr_b16 v[140:141], v67 offset:14848
	ds_read_b64_tr_b16 v[142:143], v67 offset:15360
	ds_read_b64_tr_b16 v[144:145], v67 offset:15872
	v_add_f32_e32 v191, v76, v92
	v_sub_f32_e32 v67, v78, v108
	v_pk_add_f32 v[146:147], v[190:191], v[188:189]
	v_exp_f32_e32 v78, v67
	v_sub_f32_e32 v67, v94, v108
	v_pk_add_f32 v[192:193], v[146:147], v[146:147] op_sel_hi:[0,1]
	v_cvt_pk_bf16_f32 v146, v66, v110
	v_cvt_pk_bf16_f32 v147, v68, v150
	v_cvt_pk_bf16_f32 v148, v70, v154
	v_cvt_pk_bf16_f32 v149, v72, v158
	v_exp_f32_e32 v94, v67
	v_sub_f32_e32 v67, v79, v108
	s_waitcnt lgkmcnt(0)
	v_mfma_f32_32x32x16_bf16 v[18:33], v[114:117], v[146:149], v[18:33]
	v_exp_f32_e32 v194, v67
	v_sub_f32_e32 v67, v95, v108
	v_exp_f32_e32 v192, v67
	v_sub_f32_e32 v67, v80, v108
	v_exp_f32_e32 v80, v67
	v_sub_f32_e32 v67, v81, v108
	v_exp_f32_e32 v81, v67
	v_mfma_f32_32x32x16_bf16 v[2:17], v[122:125], v[146:149], v[2:17]
	v_cvt_pk_bf16_f32 v114, v74, v186
	v_cvt_pk_bf16_f32 v115, v76, v190
	v_cvt_pk_bf16_f32 v116, v78, v194
	v_cvt_pk_bf16_f32 v117, v80, v81
	v_sub_f32_e32 v67, v96, v108
	v_exp_f32_e32 v96, v67
	v_sub_f32_e32 v67, v97, v108
	v_mfma_f32_32x32x16_bf16 v[18:33], v[118:121], v[114:117], v[18:33]
	v_exp_f32_e32 v97, v67
	v_add_f32_e32 v195, v78, v94
	v_pk_add_f32 v[118:119], v[194:195], v[192:193]
	v_add_f32_e32 v105, v80, v96
	v_pk_add_f32 v[118:119], v[118:119], v[118:119] op_sel_hi:[0,1]
	v_mov_b32_e32 v118, v97
	v_mfma_f32_32x32x16_bf16 v[2:17], v[126:129], v[114:117], v[2:17]
	v_cvt_pk_bf16_f32 v114, v82, v0
	v_cvt_pk_bf16_f32 v115, v84, v104
	v_cvt_pk_bf16_f32 v116, v86, v152
	v_cvt_pk_bf16_f32 v117, v88, v156
	v_mov_b32_e32 v104, v81
	v_pk_add_f32 v[104:105], v[104:105], v[118:119]
	v_mfma_f32_32x32x16_bf16 v[18:33], v[130:133], v[114:117], v[18:33]
	v_add_f32_e32 v0, v104, v105
	s_add_i32 s0, s43, 1
	v_fmac_f32_e32 v0, v106, v102
	s_cmp_lg_u32 s43, 5
	v_mfma_f32_32x32x16_bf16 v[2:17], v[138:141], v[114:117], v[2:17]
	v_cvt_pk_bf16_f32 v114, v90, v160
	v_cvt_pk_bf16_f32 v115, v92, v188
	v_cvt_pk_bf16_f32 v116, v94, v192
	v_cvt_pk_bf16_f32 v117, v96, v97
	s_nop 1
	v_mfma_f32_32x32x16_bf16 v[18:33], v[134:137], v[114:117], v[18:33]
	s_cselect_b32 s43, s0, 0
	v_mfma_f32_32x32x16_bf16 v[2:17], v[142:145], v[114:117], v[2:17]
	v_mov_b32_e32 v106, v0
	s_branch .LBB0_1180
